# GEMM mainloop heads aligned to 64 bytes (s_nop fill), no other change vs peel version
# speedup vs baseline: 1.0024x; 1.0024x over previous
.LBB0_211:
	s_add_i32 s60, s60, 1
	s_mov_b64 s[36:37], s[18:19]
	s_mul_i32 s18, s60, s26
	s_add_i32 s38, s18, s2
	s_cmpk_gt_i32 s38, 0x1ff
	s_cselect_b64 s[44:45], -1, 0
	s_lshl_b32 s18, s38, 3
	s_and_b32 s18, s18, 56
	s_bfe_u32 s19, s38, 0x30003
	s_mov_b32 s27, s61
	s_or_b32 s61, s18, s19
	s_mov_b32 s3, s42
	s_ashr_i32 s42, s38, 6
	s_lshl_b32 s18, s61, 19
	s_mov_b64 s[4:5], s[20:21]
	s_add_u32 s20, s14, s18
	s_addc_u32 s21, s15, 0
	s_ashr_i32 s43, s42, 31
	s_lshl_b64 s[18:19], s[42:43], 19
	s_add_u32 s18, s16, s18
	s_addc_u32 s19, s17, s19
	s_cmpk_lt_i32 s38, 0x200
	s_cselect_b32 s38, s21, s5
	s_cselect_b32 s43, s20, s4
	s_cselect_b32 s62, s19, s37
	s_cselect_b32 s63, s18, s36
	s_add_u32 s64, s36, 0x100
	s_addc_u32 s65, s37, 0
	s_mov_b32 s66, -2
	s_waitcnt lgkmcnt(0)
	s_add_u32 s36, s4, 0x100
	s_addc_u32 s37, s5, 0
	s_add_i32 s67, 0, 0x10000
	v_add_u32_e32 v1, s67, v191
	ds_read_b128 v[34:37], v1
	ds_read_b128 v[38:41], v1 offset:1024
	ds_read_b128 v[42:45], v1 offset:2048
	ds_read_b128 v[46:49], v1 offset:3072
	s_cmp_eq_u32 s66, 12
	s_cselect_b32 s49, s38, s37
	s_cselect_b32 s48, s43, s36
	s_cselect_b32 s47, s62, s65
	s_cselect_b32 s46, s63, s64
	v_lshl_add_u64 v[186:187], s[4:5], 0, v[168:169]
	s_add_i32 m0, s53, 0xc000
	ds_read_b128 v[50:53], v206
	ds_read_b128 v[58:61], v206 offset:1024
	ds_read_b128 v[62:65], v206 offset:2048
	ds_read_b128 v[66:69], v206 offset:3072
	ds_read_b128 v[170:173], v206 offset:4096
	ds_read_b128 v[174:177], v206 offset:5120
	ds_read_b128 v[178:181], v206 offset:6144
	ds_read_b128 v[182:185], v206 offset:7168
	global_load_lds_dwordx4 v[186:187], off
	v_lshl_add_u64 v[186:187], s[4:5], 0, v[166:167]
	s_add_i32 m0, s53, 0xe000
	s_nop 0
	global_load_lds_dwordx4 v[186:187], off
	s_waitcnt lgkmcnt(8)
	s_barrier
	s_waitcnt lgkmcnt(0)
	s_setprio 1
	s_waitcnt lgkmcnt(0)
	v_mfma_f32_16x16x32_bf16 v[158:161], v[34:37], v[50:53], 0
	v_mfma_f32_16x16x32_bf16 v[154:157], v[42:45], v[50:53], 0
	v_mfma_f32_16x16x32_bf16 v[142:145], v[34:37], v[62:65], 0
	v_mfma_f32_16x16x32_bf16 v[138:141], v[42:45], v[62:65], 0
	v_mfma_f32_16x16x32_bf16 v[126:129], v[34:37], v[170:173], 0
	v_mfma_f32_16x16x32_bf16 v[122:125], v[42:45], v[170:173], 0
	v_mfma_f32_16x16x32_bf16 v[110:113], v[34:37], v[178:181], 0
	v_mfma_f32_16x16x32_bf16 v[106:109], v[42:45], v[178:181], 0
	v_mfma_f32_16x16x32_bf16 v[158:161], v[38:41], v[58:61], v[158:161]
	v_mfma_f32_16x16x32_bf16 v[154:157], v[46:49], v[58:61], v[154:157]
	v_mfma_f32_16x16x32_bf16 v[142:145], v[38:41], v[66:69], v[142:145]
	v_mfma_f32_16x16x32_bf16 v[138:141], v[46:49], v[66:69], v[138:141]
	v_mfma_f32_16x16x32_bf16 v[126:129], v[38:41], v[174:177], v[126:129]
	v_mfma_f32_16x16x32_bf16 v[122:125], v[46:49], v[174:177], v[122:125]
	v_mfma_f32_16x16x32_bf16 v[110:113], v[38:41], v[182:185], v[110:113]
	v_mfma_f32_16x16x32_bf16 v[106:109], v[46:49], v[182:185], v[106:109]
	s_setprio 0
	s_barrier
	s_add_i32 s68, 0, 0x14000
	s_add_i32 s4, s67, s52
	v_add_u32_e32 v1, s68, v191
	v_lshl_add_u64 v[214:215], s[46:47], 0, v[164:165]
	s_mov_b32 m0, s4
	ds_read_b128 v[186:189], v1
	ds_read_b128 v[208:211], v1 offset:1024
	ds_read_b128 v[222:225], v1 offset:2048
	ds_read_b128 v[226:229], v1 offset:3072
	global_load_lds_dwordx4 v[214:215], off
	v_lshl_add_u64 v[238:239], s[46:47], 0, v[162:163]
	s_add_i32 m0, s4, 0x2000
	s_nop 0
	global_load_lds_dwordx4 v[238:239], off
	s_barrier
	s_waitcnt lgkmcnt(0)
	s_setprio 1
	s_waitcnt lgkmcnt(0)
	v_mfma_f32_16x16x32_bf16 v[150:153], v[186:189], v[50:53], 0
	v_mfma_f32_16x16x32_bf16 v[50:53], v[222:225], v[50:53], 0
	v_mfma_f32_16x16x32_bf16 v[150:153], v[208:211], v[58:61], v[150:153]
	v_mfma_f32_16x16x32_bf16 v[50:53], v[226:229], v[58:61], v[50:53]
	v_mfma_f32_16x16x32_bf16 v[58:61], v[186:189], v[62:65], 0
	v_mfma_f32_16x16x32_bf16 v[62:65], v[222:225], v[62:65], 0
	v_mfma_f32_16x16x32_bf16 v[114:117], v[222:225], v[170:173], 0
	v_mfma_f32_16x16x32_bf16 v[102:105], v[186:189], v[178:181], 0
	v_mfma_f32_16x16x32_bf16 v[98:101], v[222:225], v[178:181], 0
	v_mfma_f32_16x16x32_bf16 v[58:61], v[208:211], v[66:69], v[58:61]
	v_mfma_f32_16x16x32_bf16 v[62:65], v[226:229], v[66:69], v[62:65]
	v_mfma_f32_16x16x32_bf16 v[66:69], v[186:189], v[170:173], 0
	v_mfma_f32_16x16x32_bf16 v[114:117], v[226:229], v[174:177], v[114:117]
	v_mfma_f32_16x16x32_bf16 v[102:105], v[208:211], v[182:185], v[102:105]
	v_mfma_f32_16x16x32_bf16 v[98:101], v[226:229], v[182:185], v[98:101]
	v_mfma_f32_16x16x32_bf16 v[66:69], v[208:211], v[174:177], v[66:69]
	s_setprio 0
	s_mov_b32 m0, s53
	v_lshl_add_u64 v[240:241], s[48:49], 0, v[164:165]
	s_barrier
	ds_read_b128 v[118:121], v206 offset:16384
	ds_read_b128 v[130:133], v206 offset:17408
	ds_read_b128 v[134:137], v206 offset:18432
	ds_read_b128 v[146:149], v206 offset:19456
	ds_read_b128 v[170:173], v206 offset:20480
	ds_read_b128 v[174:177], v206 offset:21504
	ds_read_b128 v[178:181], v206 offset:22528
	ds_read_b128 v[182:185], v206 offset:23552
	global_load_lds_dwordx4 v[240:241], off
	v_lshl_add_u64 v[242:243], s[48:49], 0, v[162:163]
	s_mov_b32 m0, s54
	s_nop 0
	global_load_lds_dwordx4 v[242:243], off
	s_barrier
	s_waitcnt lgkmcnt(0)
	s_setprio 1
	s_waitcnt lgkmcnt(0)
	v_mfma_f32_16x16x32_bf16 v[94:97], v[34:37], v[118:121], 0
	v_mfma_f32_16x16x32_bf16 v[90:93], v[42:45], v[118:121], 0
	v_mfma_f32_16x16x32_bf16 v[78:81], v[34:37], v[134:137], 0
	v_mfma_f32_16x16x32_bf16 v[74:77], v[42:45], v[134:137], 0
	v_mfma_f32_16x16x32_bf16 v[30:33], v[34:37], v[170:173], 0
	v_mfma_f32_16x16x32_bf16 v[26:29], v[42:45], v[170:173], 0
	v_mfma_f32_16x16x32_bf16 v[14:17], v[34:37], v[178:181], 0
	v_mfma_f32_16x16x32_bf16 v[10:13], v[42:45], v[178:181], 0
	v_mfma_f32_16x16x32_bf16 v[94:97], v[38:41], v[130:133], v[94:97]
	v_mfma_f32_16x16x32_bf16 v[90:93], v[46:49], v[130:133], v[90:93]
	v_mfma_f32_16x16x32_bf16 v[78:81], v[38:41], v[146:149], v[78:81]
	v_mfma_f32_16x16x32_bf16 v[74:77], v[46:49], v[146:149], v[74:77]
	v_mfma_f32_16x16x32_bf16 v[30:33], v[38:41], v[174:177], v[30:33]
	v_mfma_f32_16x16x32_bf16 v[26:29], v[46:49], v[174:177], v[26:29]
	v_mfma_f32_16x16x32_bf16 v[14:17], v[38:41], v[182:185], v[14:17]
	v_mfma_f32_16x16x32_bf16 v[10:13], v[46:49], v[182:185], v[10:13]
	s_setprio 0
	s_barrier
	s_add_u32 s4, s46, 0x40000
	s_addc_u32 s5, s47, 0
	s_add_i32 s67, s68, s52
	v_lshl_add_u64 v[34:35], s[4:5], 0, v[164:165]
	s_mov_b32 m0, s67
	s_nop 0
	global_load_lds_dwordx4 v[34:35], off
	v_lshl_add_u64 v[34:35], s[4:5], 0, v[162:163]
	s_add_i32 m0, s67, 0x2000
	s_nop 0
	global_load_lds_dwordx4 v[34:35], off
	s_waitcnt vmcnt(6)
	s_barrier
	s_setprio 1
	v_mfma_f32_16x16x32_bf16 v[22:25], v[186:189], v[170:173], 0
	v_mfma_f32_16x16x32_bf16 v[18:21], v[222:225], v[170:173], 0
	v_mfma_f32_16x16x32_bf16 v[6:9], v[186:189], v[178:181], 0
	v_mfma_f32_16x16x32_bf16 v[2:5], v[222:225], v[178:181], 0
	v_mfma_f32_16x16x32_bf16 v[34:37], v[186:189], v[118:121], 0
	v_mfma_f32_16x16x32_bf16 v[38:41], v[222:225], v[118:121], 0
	v_mfma_f32_16x16x32_bf16 v[42:45], v[186:189], v[134:137], 0
	v_mfma_f32_16x16x32_bf16 v[46:49], v[222:225], v[134:137], 0
	v_mfma_f32_16x16x32_bf16 v[22:25], v[208:211], v[174:177], v[22:25]
	v_mfma_f32_16x16x32_bf16 v[18:21], v[226:229], v[174:177], v[18:21]
	v_mfma_f32_16x16x32_bf16 v[6:9], v[208:211], v[182:185], v[6:9]
	v_mfma_f32_16x16x32_bf16 v[2:5], v[226:229], v[182:185], v[2:5]
	v_mfma_f32_16x16x32_bf16 v[34:37], v[208:211], v[130:133], v[34:37]
	v_mfma_f32_16x16x32_bf16 v[38:41], v[226:229], v[130:133], v[38:41]
	v_mfma_f32_16x16x32_bf16 v[42:45], v[208:211], v[146:149], v[42:45]
	v_mfma_f32_16x16x32_bf16 v[46:49], v[226:229], v[146:149], v[46:49]
	s_setprio 0
	s_add_i32 s67, 0, 0x18000
	v_add_u32_e32 v1, s67, v191
	s_barrier
	ds_read_b128 v[54:57], v1
	ds_read_b128 v[70:73], v1 offset:1024
	ds_read_b128 v[82:85], v1 offset:2048
	ds_read_b128 v[86:89], v1 offset:3072
	s_add_u32 s4, s48, 0x40000
	s_addc_u32 s5, s49, 0
	s_mov_b32 m0, s55
	v_lshl_add_u64 v[134:135], s[4:5], 0, v[164:165]
	ds_read_b128 v[118:121], v206 offset:32768
	ds_read_b128 v[130:133], v206 offset:33792
	ds_read_b128 v[170:173], v206 offset:34816
	ds_read_b128 v[174:177], v206 offset:35840
	ds_read_b128 v[178:181], v206 offset:36864
	ds_read_b128 v[182:185], v206 offset:37888
	ds_read_b128 v[186:189], v206 offset:38912
	ds_read_b128 v[208:211], v206 offset:39936
	global_load_lds_dwordx4 v[134:135], off
	v_lshl_add_u64 v[134:135], s[4:5], 0, v[162:163]
	s_mov_b32 m0, s56
	s_nop 0
	global_load_lds_dwordx4 v[134:135], off
	s_waitcnt lgkmcnt(8)
	s_barrier
	s_waitcnt lgkmcnt(0)
	s_setprio 1
	s_waitcnt lgkmcnt(0)
	v_mfma_f32_16x16x32_bf16 v[134:137], v[54:57], v[118:121], v[158:161]
	v_mfma_f32_16x16x32_bf16 v[158:161], v[70:73], v[130:133], v[134:137]
	v_mfma_f32_16x16x32_bf16 v[134:137], v[82:85], v[118:121], v[154:157]
	v_mfma_f32_16x16x32_bf16 v[154:157], v[86:89], v[130:133], v[134:137]
	v_mfma_f32_16x16x32_bf16 v[134:137], v[54:57], v[170:173], v[142:145]
	v_mfma_f32_16x16x32_bf16 v[142:145], v[70:73], v[174:177], v[134:137]
	v_mfma_f32_16x16x32_bf16 v[134:137], v[82:85], v[170:173], v[138:141]
	v_mfma_f32_16x16x32_bf16 v[126:129], v[54:57], v[178:181], v[126:129]
	v_mfma_f32_16x16x32_bf16 v[122:125], v[82:85], v[178:181], v[122:125]
	v_mfma_f32_16x16x32_bf16 v[110:113], v[54:57], v[186:189], v[110:113]
	v_mfma_f32_16x16x32_bf16 v[106:109], v[82:85], v[186:189], v[106:109]
	v_mfma_f32_16x16x32_bf16 v[138:141], v[86:89], v[174:177], v[134:137]
	v_mfma_f32_16x16x32_bf16 v[126:129], v[70:73], v[182:185], v[126:129]
	v_mfma_f32_16x16x32_bf16 v[122:125], v[86:89], v[182:185], v[122:125]
	v_mfma_f32_16x16x32_bf16 v[110:113], v[70:73], v[208:211], v[110:113]
	v_mfma_f32_16x16x32_bf16 v[106:109], v[86:89], v[208:211], v[106:109]
	s_setprio 0
	s_barrier
	s_add_i32 s48, 0, 0x1c000
	s_add_i32 s4, s67, s52
	v_add_u32_e32 v1, s48, v191
	v_lshl_add_u64 v[134:135], v[214:215], 0, s[22:23]
	s_mov_b32 m0, s4
	ds_read_b128 v[222:225], v1
	ds_read_b128 v[226:229], v1 offset:1024
	ds_read_b128 v[230:233], v1 offset:2048
	ds_read_b128 v[234:237], v1 offset:3072
	global_load_lds_dwordx4 v[134:135], off
	v_lshl_add_u64 v[134:135], v[238:239], 0, s[22:23]
	s_add_i32 m0, s4, 0x2000
	s_nop 0
	global_load_lds_dwordx4 v[134:135], off
	s_barrier
	s_waitcnt lgkmcnt(0)
	s_setprio 1
	s_waitcnt lgkmcnt(0)
	v_mfma_f32_16x16x32_bf16 v[50:53], v[230:233], v[118:121], v[50:53]
	v_mfma_f32_16x16x32_bf16 v[134:137], v[222:225], v[118:121], v[150:153]
	v_mfma_f32_16x16x32_bf16 v[146:149], v[234:237], v[130:133], v[50:53]
	v_mfma_f32_16x16x32_bf16 v[50:53], v[222:225], v[170:173], v[58:61]
	v_mfma_f32_16x16x32_bf16 v[150:153], v[226:229], v[130:133], v[134:137]
	v_mfma_f32_16x16x32_bf16 v[134:137], v[226:229], v[174:177], v[50:53]
	v_mfma_f32_16x16x32_bf16 v[50:53], v[230:233], v[170:173], v[62:65]
	v_mfma_f32_16x16x32_bf16 v[130:133], v[234:237], v[174:177], v[50:53]
	v_mfma_f32_16x16x32_bf16 v[50:53], v[222:225], v[178:181], v[66:69]
	v_mfma_f32_16x16x32_bf16 v[118:121], v[226:229], v[182:185], v[50:53]
	v_mfma_f32_16x16x32_bf16 v[50:53], v[230:233], v[178:181], v[114:117]
	v_mfma_f32_16x16x32_bf16 v[114:117], v[234:237], v[182:185], v[50:53]
	v_mfma_f32_16x16x32_bf16 v[50:53], v[222:225], v[186:189], v[102:105]
	v_mfma_f32_16x16x32_bf16 v[102:105], v[226:229], v[208:211], v[50:53]
	v_mfma_f32_16x16x32_bf16 v[50:53], v[230:233], v[186:189], v[98:101]
	v_mfma_f32_16x16x32_bf16 v[98:101], v[234:237], v[208:211], v[50:53]
	s_setprio 0
	s_mov_b32 m0, s58
	v_lshl_add_u64 v[186:187], v[240:241], 0, s[22:23]
	s_barrier
	s_nop 2
	ds_read_b128 v[50:53], v206 offset:49152
	ds_read_b128 v[58:61], v206 offset:50176
	ds_read_b128 v[62:65], v206 offset:51200
	ds_read_b128 v[66:69], v206 offset:52224
	ds_read_b128 v[170:173], v206 offset:53248
	ds_read_b128 v[174:177], v206 offset:54272
	ds_read_b128 v[178:181], v206 offset:55296
	ds_read_b128 v[182:185], v206 offset:56320
	global_load_lds_dwordx4 v[186:187], off
	v_lshl_add_u64 v[186:187], v[242:243], 0, s[22:23]
	s_mov_b32 m0, s59
	s_nop 0
	global_load_lds_dwordx4 v[186:187], off
	s_barrier
	s_waitcnt lgkmcnt(0)
	s_setprio 1
	s_waitcnt lgkmcnt(0)
	v_mfma_f32_16x16x32_bf16 v[94:97], v[54:57], v[50:53], v[94:97]
	v_mfma_f32_16x16x32_bf16 v[90:93], v[82:85], v[50:53], v[90:93]
	v_mfma_f32_16x16x32_bf16 v[78:81], v[54:57], v[62:65], v[78:81]
	v_mfma_f32_16x16x32_bf16 v[74:77], v[82:85], v[62:65], v[74:77]
	v_mfma_f32_16x16x32_bf16 v[30:33], v[54:57], v[170:173], v[30:33]
	v_mfma_f32_16x16x32_bf16 v[26:29], v[82:85], v[170:173], v[26:29]
	v_mfma_f32_16x16x32_bf16 v[14:17], v[54:57], v[178:181], v[14:17]
	v_mfma_f32_16x16x32_bf16 v[10:13], v[82:85], v[178:181], v[10:13]
	v_mfma_f32_16x16x32_bf16 v[94:97], v[70:73], v[58:61], v[94:97]
	v_mfma_f32_16x16x32_bf16 v[90:93], v[86:89], v[58:61], v[90:93]
	v_mfma_f32_16x16x32_bf16 v[78:81], v[70:73], v[66:69], v[78:81]
	v_mfma_f32_16x16x32_bf16 v[74:77], v[86:89], v[66:69], v[74:77]
	v_mfma_f32_16x16x32_bf16 v[30:33], v[70:73], v[174:177], v[30:33]
	v_mfma_f32_16x16x32_bf16 v[26:29], v[86:89], v[174:177], v[26:29]
	v_mfma_f32_16x16x32_bf16 v[14:17], v[70:73], v[182:185], v[14:17]
	v_mfma_f32_16x16x32_bf16 v[10:13], v[86:89], v[182:185], v[10:13]
	s_setprio 0
	s_barrier
	s_add_u32 s4, s46, 0x40080
	s_addc_u32 s5, s47, 0
	s_add_i32 s46, s48, s52
	v_lshl_add_u64 v[54:55], s[4:5], 0, v[164:165]
	s_mov_b32 m0, s46
	s_nop 0
	global_load_lds_dwordx4 v[54:55], off
	v_lshl_add_u64 v[54:55], s[4:5], 0, v[162:163]
	s_add_i32 m0, s46, 0x2000
	s_nop 0
	global_load_lds_dwordx4 v[54:55], off
	s_waitcnt vmcnt(6)
	s_barrier
	s_setprio 1
	v_mfma_f32_16x16x32_bf16 v[34:37], v[222:225], v[50:53], v[34:37]
	v_mfma_f32_16x16x32_bf16 v[86:89], v[226:229], v[58:61], v[34:37]
	v_mfma_f32_16x16x32_bf16 v[34:37], v[230:233], v[50:53], v[38:41]
	v_mfma_f32_16x16x32_bf16 v[82:85], v[234:237], v[58:61], v[34:37]
	v_mfma_f32_16x16x32_bf16 v[34:37], v[222:225], v[62:65], v[42:45]
	v_mfma_f32_16x16x32_bf16 v[70:73], v[226:229], v[66:69], v[34:37]
	v_mfma_f32_16x16x32_bf16 v[34:37], v[230:233], v[62:65], v[46:49]
	v_mfma_f32_16x16x32_bf16 v[22:25], v[222:225], v[170:173], v[22:25]
	v_mfma_f32_16x16x32_bf16 v[18:21], v[230:233], v[170:173], v[18:21]
	v_mfma_f32_16x16x32_bf16 v[6:9], v[222:225], v[178:181], v[6:9]
	v_mfma_f32_16x16x32_bf16 v[2:5], v[230:233], v[178:181], v[2:5]
	v_mfma_f32_16x16x32_bf16 v[54:57], v[234:237], v[66:69], v[34:37]
	v_mfma_f32_16x16x32_bf16 v[22:25], v[226:229], v[174:177], v[22:25]
	v_mfma_f32_16x16x32_bf16 v[18:21], v[234:237], v[174:177], v[18:21]
	v_mfma_f32_16x16x32_bf16 v[6:9], v[226:229], v[182:185], v[6:9]
	v_mfma_f32_16x16x32_bf16 v[2:5], v[234:237], v[182:185], v[2:5]
	s_setprio 0
	s_add_i32 s66, s66, 2
	s_add_u32 s64, s64, 0x100
	s_addc_u32 s65, s65, 0
	s_cmp_gt_u32 s66, 13
	s_mov_b64 s[4:5], s[36:37]
	s_barrier
	.p2alignl 6, 3212836864

.LBB0_395:
	s_add_i32 s66, s66, 1
	s_mov_b64 s[36:37], s[20:21]
	s_mul_i32 s20, s66, s26
	s_add_i32 s42, s20, s2
	s_cmpk_gt_i32 s42, 0x3ff
	s_cselect_b64 s[52:53], -1, 0
	s_lshl_b32 s20, s42, 3
	s_and_b32 s20, s20, 56
	s_bfe_u32 s21, s42, 0x30003
	s_mov_b32 s3, s67
	s_or_b32 s67, s20, s21
	s_mov_b32 s27, s50
	s_ashr_i32 s50, s42, 6
	s_lshl_b32 s20, s67, 19
	s_mov_b64 s[4:5], s[48:49]
	s_add_u32 s48, s18, s20
	s_addc_u32 s49, s19, 0
	s_ashr_i32 s51, s50, 31
	s_lshl_b64 s[20:21], s[50:51], 19
	s_add_u32 s20, s16, s20
	s_addc_u32 s21, s17, s21
	s_cmpk_lt_i32 s42, 0x400
	s_cselect_b32 s46, s49, s5
	s_cselect_b32 s47, s48, s4
	s_cselect_b32 s51, s21, s37
	s_cselect_b32 s54, s20, s36
	s_add_u32 s55, s36, 0x100
	s_addc_u32 s56, s37, 0
	s_mov_b32 s57, -2
	s_add_u32 s36, s4, 0x100
	s_addc_u32 s37, s5, 0
	s_add_i32 s68, 0, 0x10000
	v_add_u32_e32 v30, s68, v204
	ds_read_b128 v[14:17], v30
	ds_read_b128 v[22:25], v30 offset:1024
	ds_read_b128 v[26:29], v30 offset:2048
	ds_read_b128 v[30:33], v30 offset:3072
	s_cmp_eq_u32 s57, 12
	s_cselect_b32 s45, s46, s37
	s_cselect_b32 s44, s47, s36
	s_cselect_b32 s43, s51, s56
	s_cselect_b32 s42, s54, s55
	v_lshl_add_u64 v[178:179], s[4:5], 0, v[188:189]
	s_add_i32 m0, s60, 0xc000
	ds_read_b128 v[38:41], v209
	ds_read_b128 v[42:45], v209 offset:1024
	ds_read_b128 v[46:49], v209 offset:2048
	ds_read_b128 v[54:57], v209 offset:3072
	ds_read_b128 v[58:61], v209 offset:4096
	ds_read_b128 v[62:65], v209 offset:5120
	ds_read_b128 v[66:69], v209 offset:6144
	ds_read_b128 v[70:73], v209 offset:7168
	global_load_lds_dwordx4 v[178:179], off
	v_lshl_add_u64 v[178:179], s[4:5], 0, v[186:187]
	s_add_i32 m0, s60, 0xe000
	s_nop 0
	global_load_lds_dwordx4 v[178:179], off
	s_waitcnt lgkmcnt(8)
	s_barrier
	s_waitcnt lgkmcnt(0)
	s_setprio 1
	s_waitcnt lgkmcnt(0)
	v_mfma_f32_16x16x32_bf16 v[174:177], v[14:17], v[38:41], 0
	v_mfma_f32_16x16x32_bf16 v[170:173], v[26:29], v[38:41], 0
	v_mfma_f32_16x16x32_bf16 v[158:161], v[14:17], v[46:49], 0
	v_mfma_f32_16x16x32_bf16 v[154:157], v[26:29], v[46:49], 0
	v_mfma_f32_16x16x32_bf16 v[142:145], v[14:17], v[58:61], 0
	v_mfma_f32_16x16x32_bf16 v[138:141], v[26:29], v[58:61], 0
	v_mfma_f32_16x16x32_bf16 v[126:129], v[14:17], v[66:69], 0
	v_mfma_f32_16x16x32_bf16 v[122:125], v[26:29], v[66:69], 0
	v_mfma_f32_16x16x32_bf16 v[174:177], v[22:25], v[42:45], v[174:177]
	v_mfma_f32_16x16x32_bf16 v[170:173], v[30:33], v[42:45], v[170:173]
	v_mfma_f32_16x16x32_bf16 v[158:161], v[22:25], v[54:57], v[158:161]
	v_mfma_f32_16x16x32_bf16 v[154:157], v[30:33], v[54:57], v[154:157]
	v_mfma_f32_16x16x32_bf16 v[142:145], v[22:25], v[62:65], v[142:145]
	v_mfma_f32_16x16x32_bf16 v[138:141], v[30:33], v[62:65], v[138:141]
	v_mfma_f32_16x16x32_bf16 v[126:129], v[22:25], v[70:73], v[126:129]
	v_mfma_f32_16x16x32_bf16 v[122:125], v[30:33], v[70:73], v[122:125]
	s_setprio 0
	s_barrier
	s_add_i32 s69, 0, 0x14000
	v_add_u32_e32 v210, s69, v204
	s_add_i32 s4, s68, s59
	ds_read_b128 v[178:181], v210
	ds_read_b128 v[190:193], v210 offset:1024
	ds_read_b128 v[200:203], v210 offset:2048
	ds_read_b128 v[222:225], v210 offset:3072
	v_lshl_add_u64 v[210:211], s[42:43], 0, v[184:185]
	s_mov_b32 m0, s4
	v_lshl_add_u64 v[214:215], s[42:43], 0, v[182:183]
	global_load_lds_dwordx4 v[210:211], off
	s_add_i32 m0, s4, 0x2000
	s_nop 0
	global_load_lds_dwordx4 v[214:215], off
	s_barrier
	s_waitcnt lgkmcnt(0)
	s_setprio 1
	s_waitcnt lgkmcnt(0)
	v_mfma_f32_16x16x32_bf16 v[166:169], v[178:181], v[38:41], 0
	v_mfma_f32_16x16x32_bf16 v[38:41], v[200:203], v[38:41], 0
	v_mfma_f32_16x16x32_bf16 v[166:169], v[190:193], v[42:45], v[166:169]
	v_mfma_f32_16x16x32_bf16 v[38:41], v[222:225], v[42:45], v[38:41]
	v_mfma_f32_16x16x32_bf16 v[42:45], v[178:181], v[46:49], 0
	v_mfma_f32_16x16x32_bf16 v[46:49], v[200:203], v[46:49], 0
	v_mfma_f32_16x16x32_bf16 v[42:45], v[190:193], v[54:57], v[42:45]
	v_mfma_f32_16x16x32_bf16 v[46:49], v[222:225], v[54:57], v[46:49]
	v_mfma_f32_16x16x32_bf16 v[54:57], v[178:181], v[58:61], 0
	v_mfma_f32_16x16x32_bf16 v[58:61], v[200:203], v[58:61], 0
	v_mfma_f32_16x16x32_bf16 v[54:57], v[190:193], v[62:65], v[54:57]
	v_mfma_f32_16x16x32_bf16 v[58:61], v[222:225], v[62:65], v[58:61]
	v_mfma_f32_16x16x32_bf16 v[62:65], v[178:181], v[66:69], 0
	v_mfma_f32_16x16x32_bf16 v[66:69], v[200:203], v[66:69], 0
	v_mfma_f32_16x16x32_bf16 v[62:65], v[190:193], v[70:73], v[62:65]
	v_mfma_f32_16x16x32_bf16 v[66:69], v[222:225], v[70:73], v[66:69]
	s_setprio 0
	s_mov_b32 m0, s60
	v_lshl_add_u64 v[242:243], s[44:45], 0, v[184:185]
	s_barrier
	ds_read_b128 v[70:73], v209 offset:16384
	ds_read_b128 v[114:117], v209 offset:17408
	ds_read_b128 v[118:121], v209 offset:18432
	ds_read_b128 v[130:133], v209 offset:19456
	ds_read_b128 v[134:137], v209 offset:20480
	ds_read_b128 v[146:149], v209 offset:21504
	ds_read_b128 v[150:153], v209 offset:22528
	ds_read_b128 v[162:165], v209 offset:23552
	global_load_lds_dwordx4 v[242:243], off
	v_lshl_add_u64 v[244:245], s[44:45], 0, v[182:183]
	s_mov_b32 m0, s61
	s_nop 0
	global_load_lds_dwordx4 v[244:245], off
	s_barrier
	s_waitcnt lgkmcnt(0)
	s_setprio 1
	s_waitcnt lgkmcnt(0)
	v_mfma_f32_16x16x32_bf16 v[110:113], v[14:17], v[70:73], 0
	v_mfma_f32_16x16x32_bf16 v[106:109], v[26:29], v[70:73], 0
	v_mfma_f32_16x16x32_bf16 v[94:97], v[14:17], v[118:121], 0
	v_mfma_f32_16x16x32_bf16 v[90:93], v[26:29], v[118:121], 0
	v_mfma_f32_16x16x32_bf16 v[78:81], v[14:17], v[134:137], 0
	v_mfma_f32_16x16x32_bf16 v[74:77], v[26:29], v[134:137], 0
	v_mfma_f32_16x16x32_bf16 v[10:13], v[26:29], v[150:153], 0
	v_mfma_f32_16x16x32_bf16 v[110:113], v[22:25], v[114:117], v[110:113]
	v_mfma_f32_16x16x32_bf16 v[106:109], v[30:33], v[114:117], v[106:109]
	v_mfma_f32_16x16x32_bf16 v[94:97], v[22:25], v[130:133], v[94:97]
	v_mfma_f32_16x16x32_bf16 v[90:93], v[30:33], v[130:133], v[90:93]
	v_mfma_f32_16x16x32_bf16 v[78:81], v[22:25], v[146:149], v[78:81]
	v_mfma_f32_16x16x32_bf16 v[74:77], v[30:33], v[146:149], v[74:77]
	v_mfma_f32_16x16x32_bf16 v[14:17], v[14:17], v[150:153], 0
	v_mfma_f32_16x16x32_bf16 v[10:13], v[30:33], v[162:165], v[10:13]
	v_mfma_f32_16x16x32_bf16 v[14:17], v[22:25], v[162:165], v[14:17]
	s_setprio 0
	s_barrier
	s_add_u32 s4, s42, 0x40000
	s_addc_u32 s5, s43, 0
	s_add_i32 s68, s69, s59
	v_lshl_add_u64 v[18:19], s[4:5], 0, v[184:185]
	s_mov_b32 m0, s68
	s_nop 0
	global_load_lds_dwordx4 v[18:19], off
	v_lshl_add_u64 v[18:19], s[4:5], 0, v[182:183]
	s_add_i32 m0, s68, 0x2000
	s_nop 0
	global_load_lds_dwordx4 v[18:19], off
	s_waitcnt vmcnt(6)
	s_barrier
	s_setprio 1
	v_mfma_f32_16x16x32_bf16 v[18:21], v[178:181], v[70:73], 0
	v_mfma_f32_16x16x32_bf16 v[22:25], v[190:193], v[114:117], v[18:21]
	v_mfma_f32_16x16x32_bf16 v[18:21], v[200:203], v[70:73], 0
	v_mfma_f32_16x16x32_bf16 v[26:29], v[222:225], v[114:117], v[18:21]
	v_mfma_f32_16x16x32_bf16 v[18:21], v[178:181], v[118:121], 0
	v_mfma_f32_16x16x32_bf16 v[30:33], v[190:193], v[130:133], v[18:21]
	v_mfma_f32_16x16x32_bf16 v[18:21], v[200:203], v[118:121], 0
	v_mfma_f32_16x16x32_bf16 v[70:73], v[222:225], v[130:133], v[18:21]
	v_mfma_f32_16x16x32_bf16 v[18:21], v[178:181], v[134:137], 0
	v_mfma_f32_16x16x32_bf16 v[50:53], v[190:193], v[146:149], v[18:21]
	v_mfma_f32_16x16x32_bf16 v[18:21], v[200:203], v[134:137], 0
	v_mfma_f32_16x16x32_bf16 v[6:9], v[178:181], v[150:153], 0
	v_mfma_f32_16x16x32_bf16 v[2:5], v[200:203], v[150:153], 0
	v_mfma_f32_16x16x32_bf16 v[34:37], v[222:225], v[146:149], v[18:21]
	v_mfma_f32_16x16x32_bf16 v[6:9], v[190:193], v[162:165], v[6:9]
	v_mfma_f32_16x16x32_bf16 v[2:5], v[222:225], v[162:165], v[2:5]
	s_setprio 0
	s_add_i32 s68, 0, 0x18000
	v_add_u32_e32 v98, s68, v204
	s_barrier
	ds_read_b128 v[18:21], v98
	ds_read_b128 v[82:85], v98 offset:1024
	ds_read_b128 v[86:89], v98 offset:2048
	ds_read_b128 v[98:101], v98 offset:3072
	s_add_u32 s4, s44, 0x40000
	s_addc_u32 s5, s45, 0
	s_mov_b32 m0, s62
	v_lshl_add_u64 v[134:135], s[4:5], 0, v[184:185]
	ds_read_b128 v[102:105], v209 offset:32768
	ds_read_b128 v[114:117], v209 offset:33792
	ds_read_b128 v[118:121], v209 offset:34816
	ds_read_b128 v[130:133], v209 offset:35840
	ds_read_b128 v[178:181], v209 offset:36864
	ds_read_b128 v[190:193], v209 offset:37888
	ds_read_b128 v[200:203], v209 offset:38912
	ds_read_b128 v[222:225], v209 offset:39936
	global_load_lds_dwordx4 v[134:135], off
	v_lshl_add_u64 v[134:135], s[4:5], 0, v[182:183]
	s_mov_b32 m0, s63
	s_nop 0
	global_load_lds_dwordx4 v[134:135], off
	s_waitcnt lgkmcnt(8)
	s_barrier
	s_waitcnt lgkmcnt(0)
	s_setprio 1
	s_waitcnt lgkmcnt(0)
	v_mfma_f32_16x16x32_bf16 v[134:137], v[18:21], v[102:105], v[174:177]
	v_mfma_f32_16x16x32_bf16 v[174:177], v[82:85], v[114:117], v[134:137]
	v_mfma_f32_16x16x32_bf16 v[134:137], v[86:89], v[102:105], v[170:173]
	v_mfma_f32_16x16x32_bf16 v[170:173], v[98:101], v[114:117], v[134:137]
	v_mfma_f32_16x16x32_bf16 v[134:137], v[18:21], v[118:121], v[158:161]
	v_mfma_f32_16x16x32_bf16 v[158:161], v[82:85], v[130:133], v[134:137]
	v_mfma_f32_16x16x32_bf16 v[134:137], v[86:89], v[118:121], v[154:157]
	v_mfma_f32_16x16x32_bf16 v[154:157], v[98:101], v[130:133], v[134:137]
	v_mfma_f32_16x16x32_bf16 v[134:137], v[18:21], v[178:181], v[142:145]
	v_mfma_f32_16x16x32_bf16 v[142:145], v[82:85], v[190:193], v[134:137]
	v_mfma_f32_16x16x32_bf16 v[134:137], v[86:89], v[178:181], v[138:141]
	v_mfma_f32_16x16x32_bf16 v[126:129], v[18:21], v[200:203], v[126:129]
	v_mfma_f32_16x16x32_bf16 v[122:125], v[86:89], v[200:203], v[122:125]
	v_mfma_f32_16x16x32_bf16 v[138:141], v[98:101], v[190:193], v[134:137]
	v_mfma_f32_16x16x32_bf16 v[126:129], v[82:85], v[222:225], v[126:129]
	v_mfma_f32_16x16x32_bf16 v[122:125], v[98:101], v[222:225], v[122:125]
	s_setprio 0
	s_barrier
	s_add_i32 s44, 0, 0x1c000
	v_add_u32_e32 v134, s44, v204
	s_add_i32 s4, s68, s59
	ds_read_b128 v[226:229], v134
	ds_read_b128 v[230:233], v134 offset:1024
	ds_read_b128 v[234:237], v134 offset:2048
	ds_read_b128 v[238:241], v134 offset:3072
	v_lshl_add_u64 v[134:135], v[210:211], 0, s[22:23]
	s_mov_b32 m0, s4
	s_nop 0
	global_load_lds_dwordx4 v[134:135], off
	v_lshl_add_u64 v[134:135], v[214:215], 0, s[22:23]
	s_add_i32 m0, s4, 0x2000
	s_nop 0
	global_load_lds_dwordx4 v[134:135], off
	s_barrier
	s_waitcnt lgkmcnt(0)
	s_setprio 1
	s_waitcnt lgkmcnt(0)
	v_mfma_f32_16x16x32_bf16 v[38:41], v[234:237], v[102:105], v[38:41]
	v_mfma_f32_16x16x32_bf16 v[162:165], v[238:241], v[114:117], v[38:41]
	v_mfma_f32_16x16x32_bf16 v[38:41], v[226:229], v[118:121], v[42:45]
	v_mfma_f32_16x16x32_bf16 v[150:153], v[230:233], v[130:133], v[38:41]
	v_mfma_f32_16x16x32_bf16 v[38:41], v[234:237], v[118:121], v[46:49]
	v_mfma_f32_16x16x32_bf16 v[134:137], v[226:229], v[102:105], v[166:169]
	v_mfma_f32_16x16x32_bf16 v[146:149], v[238:241], v[130:133], v[38:41]
	v_mfma_f32_16x16x32_bf16 v[38:41], v[226:229], v[178:181], v[54:57]
	v_mfma_f32_16x16x32_bf16 v[166:169], v[230:233], v[114:117], v[134:137]
	v_mfma_f32_16x16x32_bf16 v[134:137], v[230:233], v[190:193], v[38:41]
	v_mfma_f32_16x16x32_bf16 v[38:41], v[234:237], v[178:181], v[58:61]
	v_mfma_f32_16x16x32_bf16 v[130:133], v[238:241], v[190:193], v[38:41]
	v_mfma_f32_16x16x32_bf16 v[38:41], v[226:229], v[200:203], v[62:65]
	v_mfma_f32_16x16x32_bf16 v[118:121], v[230:233], v[222:225], v[38:41]
	v_mfma_f32_16x16x32_bf16 v[38:41], v[234:237], v[200:203], v[66:69]
	v_mfma_f32_16x16x32_bf16 v[114:117], v[238:241], v[222:225], v[38:41]
	s_setprio 0
	s_mov_b32 m0, s64
	v_lshl_add_u64 v[102:103], v[242:243], 0, s[22:23]
	s_barrier
	s_nop 2
	ds_read_b128 v[38:41], v209 offset:49152
	ds_read_b128 v[42:45], v209 offset:50176
	ds_read_b128 v[46:49], v209 offset:51200
	ds_read_b128 v[54:57], v209 offset:52224
	ds_read_b128 v[58:61], v209 offset:53248
	ds_read_b128 v[62:65], v209 offset:54272
	ds_read_b128 v[66:69], v209 offset:55296
	ds_read_b128 v[178:181], v209 offset:56320
	global_load_lds_dwordx4 v[102:103], off
	v_lshl_add_u64 v[102:103], v[244:245], 0, s[22:23]
	s_mov_b32 m0, s65
	s_nop 0
	global_load_lds_dwordx4 v[102:103], off
	s_barrier
	s_waitcnt lgkmcnt(0)
	s_setprio 1
	s_waitcnt lgkmcnt(0)
	v_mfma_f32_16x16x32_bf16 v[102:105], v[18:21], v[38:41], v[110:113]
	v_mfma_f32_16x16x32_bf16 v[110:113], v[82:85], v[42:45], v[102:105]
	v_mfma_f32_16x16x32_bf16 v[102:105], v[86:89], v[38:41], v[106:109]
	v_mfma_f32_16x16x32_bf16 v[94:97], v[18:21], v[46:49], v[94:97]
	v_mfma_f32_16x16x32_bf16 v[90:93], v[86:89], v[46:49], v[90:93]
	v_mfma_f32_16x16x32_bf16 v[78:81], v[18:21], v[58:61], v[78:81]
	v_mfma_f32_16x16x32_bf16 v[74:77], v[86:89], v[58:61], v[74:77]
	v_mfma_f32_16x16x32_bf16 v[14:17], v[18:21], v[66:69], v[14:17]
	v_mfma_f32_16x16x32_bf16 v[10:13], v[86:89], v[66:69], v[10:13]
	v_mfma_f32_16x16x32_bf16 v[106:109], v[98:101], v[42:45], v[102:105]
	v_mfma_f32_16x16x32_bf16 v[94:97], v[82:85], v[54:57], v[94:97]
	v_mfma_f32_16x16x32_bf16 v[90:93], v[98:101], v[54:57], v[90:93]
	v_mfma_f32_16x16x32_bf16 v[78:81], v[82:85], v[62:65], v[78:81]
	v_mfma_f32_16x16x32_bf16 v[74:77], v[98:101], v[62:65], v[74:77]
	v_mfma_f32_16x16x32_bf16 v[18:21], v[82:85], v[178:181], v[14:17]
	v_mfma_f32_16x16x32_bf16 v[10:13], v[98:101], v[178:181], v[10:13]
	s_setprio 0
	s_barrier
	s_add_u32 s4, s42, 0x40080
	s_addc_u32 s5, s43, 0
	s_add_i32 s42, s44, s59
	v_lshl_add_u64 v[14:15], s[4:5], 0, v[184:185]
	s_mov_b32 m0, s42
	s_nop 0
	global_load_lds_dwordx4 v[14:15], off
	v_lshl_add_u64 v[14:15], s[4:5], 0, v[182:183]
	s_add_i32 m0, s42, 0x2000
	s_nop 0
	global_load_lds_dwordx4 v[14:15], off
	s_waitcnt vmcnt(6)
	s_barrier
	s_setprio 1
	v_mfma_f32_16x16x32_bf16 v[14:17], v[226:229], v[38:41], v[22:25]
	v_mfma_f32_16x16x32_bf16 v[102:105], v[230:233], v[42:45], v[14:17]
	v_mfma_f32_16x16x32_bf16 v[14:17], v[234:237], v[38:41], v[26:29]
	v_mfma_f32_16x16x32_bf16 v[98:101], v[238:241], v[42:45], v[14:17]
	v_mfma_f32_16x16x32_bf16 v[14:17], v[226:229], v[46:49], v[30:33]
	v_mfma_f32_16x16x32_bf16 v[86:89], v[230:233], v[54:57], v[14:17]
	v_mfma_f32_16x16x32_bf16 v[14:17], v[234:237], v[46:49], v[70:73]
	v_mfma_f32_16x16x32_bf16 v[82:85], v[238:241], v[54:57], v[14:17]
	v_mfma_f32_16x16x32_bf16 v[14:17], v[226:229], v[58:61], v[50:53]
	v_mfma_f32_16x16x32_bf16 v[50:53], v[230:233], v[62:65], v[14:17]
	v_mfma_f32_16x16x32_bf16 v[14:17], v[234:237], v[58:61], v[34:37]
	v_mfma_f32_16x16x32_bf16 v[6:9], v[226:229], v[66:69], v[6:9]
	v_mfma_f32_16x16x32_bf16 v[2:5], v[234:237], v[66:69], v[2:5]
	v_mfma_f32_16x16x32_bf16 v[34:37], v[238:241], v[62:65], v[14:17]
	v_mfma_f32_16x16x32_bf16 v[6:9], v[230:233], v[178:181], v[6:9]
	v_mfma_f32_16x16x32_bf16 v[2:5], v[238:241], v[178:181], v[2:5]
	s_setprio 0
	s_add_i32 s57, s57, 2
	s_add_u32 s55, s55, 0x100
	s_addc_u32 s56, s56, 0
	s_cmp_gt_u32 s57, 13
	s_mov_b64 s[4:5], s[36:37]
	s_barrier
	.p2alignl 6, 3212836864

.LBB0_1098:
	s_add_i32 s76, s76, 1
	s_mov_b64 s[62:63], s[54:55]
	s_mul_i32 s54, s76, s26
	s_add_i32 s64, s54, s2
	s_cmpk_gt_i32 s64, 0x57f
	s_cselect_b64 s[60:61], -1, 0
	s_lshl_b32 s54, s64, 3
	s_and_b32 s54, s54, 56
	s_bfe_u32 s55, s64, 0x30003
	s_or_b32 s77, s54, s55
	s_ashr_i32 s58, s64, 6
	s_lshl_b32 s54, s77, 19
	s_mov_b64 s[36:37], s[56:57]
	s_add_u32 s56, s52, s54
	s_addc_u32 s57, s53, 0
	s_ashr_i32 s59, s58, 31
	s_lshl_b64 s[54:55], s[58:59], 19
	s_add_u32 s54, s4, s54
	s_addc_u32 s55, s5, s55
	s_cmpk_lt_i32 s64, 0x580
	s_cselect_b32 s59, s57, s37
	s_cselect_b32 s78, s56, s36
	s_cselect_b32 s79, s55, s63
	s_cselect_b32 s80, s54, s62
	s_add_u32 s81, s62, 0x100
	s_addc_u32 s82, s63, 0
	s_mov_b32 s83, -2
	s_add_u32 s62, s36, 0x100
	s_addc_u32 s63, s37, 0
	s_add_i32 s84, 0, 0x10000
	v_add_u32_e32 v70, s84, v170
	ds_read_b128 v[58:61], v70
	ds_read_b128 v[62:65], v70 offset:1024
	ds_read_b128 v[66:69], v70 offset:2048
	ds_read_b128 v[70:73], v70 offset:3072
	s_cmp_eq_u32 s83, 12
	s_cselect_b32 s67, s59, s63
	s_cselect_b32 s66, s78, s62
	s_cselect_b32 s65, s79, s82
	s_cselect_b32 s64, s80, s81
	v_lshl_add_u64 v[192:193], s[36:37], 0, v[168:169]
	s_add_i32 m0, s69, 0xc000
	ds_read_b128 v[78:81], v175
	ds_read_b128 v[86:89], v175 offset:1024
	ds_read_b128 v[90:93], v175 offset:2048
	ds_read_b128 v[94:97], v175 offset:3072
	ds_read_b128 v[176:179], v175 offset:4096
	ds_read_b128 v[180:183], v175 offset:5120
	ds_read_b128 v[184:187], v175 offset:6144
	ds_read_b128 v[188:191], v175 offset:7168
	global_load_lds_dwordx4 v[192:193], off
	v_lshl_add_u64 v[192:193], s[36:37], 0, v[166:167]
	s_add_i32 m0, s69, 0xe000
	s_nop 0
	global_load_lds_dwordx4 v[192:193], off
	s_waitcnt lgkmcnt(8)
	s_barrier
	s_waitcnt lgkmcnt(0)
	s_setprio 1
	s_waitcnt lgkmcnt(0)
	v_mfma_f32_16x16x32_bf16 v[158:161], v[58:61], v[78:81], 0
	v_mfma_f32_16x16x32_bf16 v[150:153], v[66:69], v[78:81], 0
	v_mfma_f32_16x16x32_bf16 v[142:145], v[58:61], v[90:93], 0
	v_mfma_f32_16x16x32_bf16 v[134:137], v[66:69], v[90:93], 0
	v_mfma_f32_16x16x32_bf16 v[126:129], v[58:61], v[176:179], 0
	v_mfma_f32_16x16x32_bf16 v[118:121], v[66:69], v[176:179], 0
	v_mfma_f32_16x16x32_bf16 v[110:113], v[58:61], v[184:187], 0
	v_mfma_f32_16x16x32_bf16 v[102:105], v[66:69], v[184:187], 0
	v_mfma_f32_16x16x32_bf16 v[158:161], v[62:65], v[86:89], v[158:161]
	v_mfma_f32_16x16x32_bf16 v[150:153], v[70:73], v[86:89], v[150:153]
	v_mfma_f32_16x16x32_bf16 v[142:145], v[62:65], v[94:97], v[142:145]
	v_mfma_f32_16x16x32_bf16 v[134:137], v[70:73], v[94:97], v[134:137]
	v_mfma_f32_16x16x32_bf16 v[126:129], v[62:65], v[180:183], v[126:129]
	v_mfma_f32_16x16x32_bf16 v[118:121], v[70:73], v[180:183], v[118:121]
	v_mfma_f32_16x16x32_bf16 v[110:113], v[62:65], v[188:191], v[110:113]
	v_mfma_f32_16x16x32_bf16 v[102:105], v[70:73], v[188:191], v[102:105]
	s_setprio 0
	s_barrier
	s_add_i32 s85, 0, 0x14000
	v_add_u32_e32 v192, s85, v170
	s_add_i32 s36, s84, s68
	ds_read_b128 v[200:203], v192
	ds_read_b128 v[204:207], v192 offset:1024
	ds_read_b128 v[208:211], v192 offset:2048
	ds_read_b128 v[222:225], v192 offset:3072
	v_lshl_add_u64 v[192:193], s[64:65], 0, v[164:165]
	s_mov_b32 m0, s36
	v_lshl_add_u64 v[214:215], s[64:65], 0, v[162:163]
	global_load_lds_dwordx4 v[192:193], off
	s_add_i32 m0, s36, 0x2000
	s_nop 0
	global_load_lds_dwordx4 v[214:215], off
	s_barrier
	s_waitcnt lgkmcnt(0)
	s_setprio 1
	s_waitcnt lgkmcnt(0)
	v_mfma_f32_16x16x32_bf16 v[154:157], v[200:203], v[78:81], 0
	v_mfma_f32_16x16x32_bf16 v[78:81], v[208:211], v[78:81], 0
	v_mfma_f32_16x16x32_bf16 v[154:157], v[204:207], v[86:89], v[154:157]
	v_mfma_f32_16x16x32_bf16 v[78:81], v[222:225], v[86:89], v[78:81]
	v_mfma_f32_16x16x32_bf16 v[86:89], v[200:203], v[90:93], 0
	v_mfma_f32_16x16x32_bf16 v[90:93], v[208:211], v[90:93], 0
	v_mfma_f32_16x16x32_bf16 v[114:117], v[208:211], v[176:179], 0
	v_mfma_f32_16x16x32_bf16 v[106:109], v[200:203], v[184:187], 0
	v_mfma_f32_16x16x32_bf16 v[98:101], v[208:211], v[184:187], 0
	v_mfma_f32_16x16x32_bf16 v[86:89], v[204:207], v[94:97], v[86:89]
	v_mfma_f32_16x16x32_bf16 v[90:93], v[222:225], v[94:97], v[90:93]
	v_mfma_f32_16x16x32_bf16 v[94:97], v[200:203], v[176:179], 0
	v_mfma_f32_16x16x32_bf16 v[114:117], v[222:225], v[180:183], v[114:117]
	v_mfma_f32_16x16x32_bf16 v[106:109], v[204:207], v[188:191], v[106:109]
	v_mfma_f32_16x16x32_bf16 v[98:101], v[222:225], v[188:191], v[98:101]
	v_mfma_f32_16x16x32_bf16 v[94:97], v[204:207], v[180:183], v[94:97]
	s_setprio 0
	s_mov_b32 m0, s69
	v_lshl_add_u64 v[234:235], s[66:67], 0, v[164:165]
	s_barrier
	ds_read_b128 v[122:125], v175 offset:16384
	ds_read_b128 v[130:133], v175 offset:17408
	ds_read_b128 v[138:141], v175 offset:18432
	ds_read_b128 v[146:149], v175 offset:19456
	ds_read_b128 v[176:179], v175 offset:20480
	ds_read_b128 v[180:183], v175 offset:21504
	ds_read_b128 v[184:187], v175 offset:22528
	ds_read_b128 v[188:191], v175 offset:23552
	global_load_lds_dwordx4 v[234:235], off
	v_lshl_add_u64 v[236:237], s[66:67], 0, v[162:163]
	s_mov_b32 m0, s70
	s_nop 0
	global_load_lds_dwordx4 v[236:237], off
	s_barrier
	s_waitcnt lgkmcnt(0)
	s_setprio 1
	s_waitcnt lgkmcnt(0)
	v_mfma_f32_16x16x32_bf16 v[82:85], v[58:61], v[122:125], 0
	v_mfma_f32_16x16x32_bf16 v[54:57], v[66:69], v[122:125], 0
	v_mfma_f32_16x16x32_bf16 v[46:49], v[58:61], v[138:141], 0
	v_mfma_f32_16x16x32_bf16 v[38:41], v[66:69], v[138:141], 0
	v_mfma_f32_16x16x32_bf16 v[30:33], v[58:61], v[176:179], 0
	v_mfma_f32_16x16x32_bf16 v[22:25], v[66:69], v[176:179], 0
	v_mfma_f32_16x16x32_bf16 v[14:17], v[58:61], v[184:187], 0
	v_mfma_f32_16x16x32_bf16 v[6:9], v[66:69], v[184:187], 0
	v_mfma_f32_16x16x32_bf16 v[82:85], v[62:65], v[130:133], v[82:85]
	v_mfma_f32_16x16x32_bf16 v[54:57], v[70:73], v[130:133], v[54:57]
	v_mfma_f32_16x16x32_bf16 v[46:49], v[62:65], v[146:149], v[46:49]
	v_mfma_f32_16x16x32_bf16 v[38:41], v[70:73], v[146:149], v[38:41]
	v_mfma_f32_16x16x32_bf16 v[30:33], v[62:65], v[180:183], v[30:33]
	v_mfma_f32_16x16x32_bf16 v[22:25], v[70:73], v[180:183], v[22:25]
	v_mfma_f32_16x16x32_bf16 v[14:17], v[62:65], v[188:191], v[14:17]
	v_mfma_f32_16x16x32_bf16 v[6:9], v[70:73], v[188:191], v[6:9]
	s_setprio 0
	s_barrier
	s_add_u32 s36, s64, 0x40000
	s_addc_u32 s37, s65, 0
	s_add_i32 s84, s85, s68
	v_lshl_add_u64 v[58:59], s[36:37], 0, v[164:165]
	s_mov_b32 m0, s84
	s_nop 0
	global_load_lds_dwordx4 v[58:59], off
	v_lshl_add_u64 v[58:59], s[36:37], 0, v[162:163]
	s_add_i32 m0, s84, 0x2000
	s_nop 0
	global_load_lds_dwordx4 v[58:59], off
	s_waitcnt vmcnt(6)
	s_barrier
	s_setprio 1
	v_mfma_f32_16x16x32_bf16 v[50:53], v[208:211], v[122:125], 0
	v_mfma_f32_16x16x32_bf16 v[42:45], v[200:203], v[138:141], 0
	v_mfma_f32_16x16x32_bf16 v[34:37], v[208:211], v[138:141], 0
	v_mfma_f32_16x16x32_bf16 v[26:29], v[200:203], v[176:179], 0
	v_mfma_f32_16x16x32_bf16 v[18:21], v[208:211], v[176:179], 0
	v_mfma_f32_16x16x32_bf16 v[10:13], v[200:203], v[184:187], 0
	v_mfma_f32_16x16x32_bf16 v[2:5], v[208:211], v[184:187], 0
	v_mfma_f32_16x16x32_bf16 v[58:61], v[200:203], v[122:125], 0
	v_mfma_f32_16x16x32_bf16 v[50:53], v[222:225], v[130:133], v[50:53]
	v_mfma_f32_16x16x32_bf16 v[42:45], v[204:207], v[146:149], v[42:45]
	v_mfma_f32_16x16x32_bf16 v[34:37], v[222:225], v[146:149], v[34:37]
	v_mfma_f32_16x16x32_bf16 v[26:29], v[204:207], v[180:183], v[26:29]
	v_mfma_f32_16x16x32_bf16 v[18:21], v[222:225], v[180:183], v[18:21]
	v_mfma_f32_16x16x32_bf16 v[10:13], v[204:207], v[188:191], v[10:13]
	v_mfma_f32_16x16x32_bf16 v[2:5], v[222:225], v[188:191], v[2:5]
	v_mfma_f32_16x16x32_bf16 v[58:61], v[204:207], v[130:133], v[58:61]
	s_setprio 0
	s_add_i32 s84, 0, 0x18000
	v_add_u32_e32 v74, s84, v170
	s_barrier
	ds_read_b128 v[62:65], v74
	ds_read_b128 v[66:69], v74 offset:1024
	ds_read_b128 v[70:73], v74 offset:2048
	ds_read_b128 v[74:77], v74 offset:3072
	s_add_u32 s36, s66, 0x40000
	s_addc_u32 s37, s67, 0
	s_mov_b32 m0, s71
	v_lshl_add_u64 v[138:139], s[36:37], 0, v[164:165]
	ds_read_b128 v[122:125], v175 offset:32768
	ds_read_b128 v[130:133], v175 offset:33792
	ds_read_b128 v[176:179], v175 offset:34816
	ds_read_b128 v[180:183], v175 offset:35840
	ds_read_b128 v[184:187], v175 offset:36864
	ds_read_b128 v[188:191], v175 offset:37888
	ds_read_b128 v[200:203], v175 offset:38912
	ds_read_b128 v[204:207], v175 offset:39936
	global_load_lds_dwordx4 v[138:139], off
	v_lshl_add_u64 v[138:139], s[36:37], 0, v[162:163]
	s_mov_b32 m0, s72
	s_nop 0
	global_load_lds_dwordx4 v[138:139], off
	s_waitcnt lgkmcnt(8)
	s_barrier
	s_waitcnt lgkmcnt(0)
	s_setprio 1
	s_waitcnt lgkmcnt(0)
	v_mfma_f32_16x16x32_bf16 v[138:141], v[62:65], v[122:125], v[158:161]
	v_mfma_f32_16x16x32_bf16 v[158:161], v[66:69], v[130:133], v[138:141]
	v_mfma_f32_16x16x32_bf16 v[138:141], v[70:73], v[122:125], v[150:153]
	v_mfma_f32_16x16x32_bf16 v[150:153], v[74:77], v[130:133], v[138:141]
	v_mfma_f32_16x16x32_bf16 v[138:141], v[62:65], v[176:179], v[142:145]
	v_mfma_f32_16x16x32_bf16 v[134:137], v[70:73], v[176:179], v[134:137]
	v_mfma_f32_16x16x32_bf16 v[126:129], v[62:65], v[184:187], v[126:129]
	v_mfma_f32_16x16x32_bf16 v[118:121], v[70:73], v[184:187], v[118:121]
	v_mfma_f32_16x16x32_bf16 v[110:113], v[62:65], v[200:203], v[110:113]
	v_mfma_f32_16x16x32_bf16 v[102:105], v[70:73], v[200:203], v[102:105]
	v_mfma_f32_16x16x32_bf16 v[142:145], v[66:69], v[180:183], v[138:141]
	v_mfma_f32_16x16x32_bf16 v[134:137], v[74:77], v[180:183], v[134:137]
	v_mfma_f32_16x16x32_bf16 v[126:129], v[66:69], v[188:191], v[126:129]
	v_mfma_f32_16x16x32_bf16 v[118:121], v[74:77], v[188:191], v[118:121]
	v_mfma_f32_16x16x32_bf16 v[110:113], v[66:69], v[204:207], v[110:113]
	v_mfma_f32_16x16x32_bf16 v[102:105], v[74:77], v[204:207], v[102:105]
	s_setprio 0
	s_barrier
	s_add_i32 s66, 0, 0x1c000
	v_add_u32_e32 v138, s66, v170
	s_add_i32 s36, s84, s68
	ds_read_b128 v[208:211], v138
	ds_read_b128 v[222:225], v138 offset:1024
	ds_read_b128 v[226:229], v138 offset:2048
	ds_read_b128 v[230:233], v138 offset:3072
	v_lshl_add_u64 v[138:139], v[192:193], 0, s[22:23]
	s_mov_b32 m0, s36
	s_nop 0
	global_load_lds_dwordx4 v[138:139], off
	v_lshl_add_u64 v[138:139], v[214:215], 0, s[22:23]
	s_add_i32 m0, s36, 0x2000
	s_nop 0
	global_load_lds_dwordx4 v[138:139], off
	s_barrier
	s_waitcnt lgkmcnt(0)
	s_setprio 1
	s_waitcnt lgkmcnt(0)
	v_mfma_f32_16x16x32_bf16 v[78:81], v[226:229], v[122:125], v[78:81]
	v_mfma_f32_16x16x32_bf16 v[138:141], v[208:211], v[122:125], v[154:157]
	v_mfma_f32_16x16x32_bf16 v[146:149], v[230:233], v[130:133], v[78:81]
	v_mfma_f32_16x16x32_bf16 v[78:81], v[208:211], v[176:179], v[86:89]
	v_mfma_f32_16x16x32_bf16 v[154:157], v[222:225], v[130:133], v[138:141]
	v_mfma_f32_16x16x32_bf16 v[138:141], v[222:225], v[180:183], v[78:81]
	v_mfma_f32_16x16x32_bf16 v[78:81], v[226:229], v[176:179], v[90:93]
	v_mfma_f32_16x16x32_bf16 v[130:133], v[230:233], v[180:183], v[78:81]
	v_mfma_f32_16x16x32_bf16 v[78:81], v[208:211], v[184:187], v[94:97]
	v_mfma_f32_16x16x32_bf16 v[122:125], v[222:225], v[188:191], v[78:81]
	v_mfma_f32_16x16x32_bf16 v[78:81], v[226:229], v[184:187], v[114:117]
	v_mfma_f32_16x16x32_bf16 v[114:117], v[230:233], v[188:191], v[78:81]
	v_mfma_f32_16x16x32_bf16 v[78:81], v[208:211], v[200:203], v[106:109]
	v_mfma_f32_16x16x32_bf16 v[106:109], v[222:225], v[204:207], v[78:81]
	v_mfma_f32_16x16x32_bf16 v[78:81], v[226:229], v[200:203], v[98:101]
	v_mfma_f32_16x16x32_bf16 v[98:101], v[230:233], v[204:207], v[78:81]
	s_setprio 0
	s_mov_b32 m0, s73
	v_lshl_add_u64 v[192:193], v[234:235], 0, s[22:23]
	s_barrier
	s_nop 2
	ds_read_b128 v[78:81], v175 offset:49152
	ds_read_b128 v[86:89], v175 offset:50176
	ds_read_b128 v[90:93], v175 offset:51200
	ds_read_b128 v[94:97], v175 offset:52224
	ds_read_b128 v[176:179], v175 offset:53248
	ds_read_b128 v[180:183], v175 offset:54272
	ds_read_b128 v[184:187], v175 offset:55296
	ds_read_b128 v[188:191], v175 offset:56320
	global_load_lds_dwordx4 v[192:193], off
	v_lshl_add_u64 v[192:193], v[236:237], 0, s[22:23]
	s_mov_b32 m0, s75
	s_nop 0
	global_load_lds_dwordx4 v[192:193], off
	s_barrier
	s_waitcnt lgkmcnt(0)
	s_setprio 1
	s_waitcnt lgkmcnt(0)
	v_mfma_f32_16x16x32_bf16 v[82:85], v[62:65], v[78:81], v[82:85]
	v_mfma_f32_16x16x32_bf16 v[54:57], v[70:73], v[78:81], v[54:57]
	v_mfma_f32_16x16x32_bf16 v[46:49], v[62:65], v[90:93], v[46:49]
	v_mfma_f32_16x16x32_bf16 v[38:41], v[70:73], v[90:93], v[38:41]
	v_mfma_f32_16x16x32_bf16 v[30:33], v[62:65], v[176:179], v[30:33]
	v_mfma_f32_16x16x32_bf16 v[22:25], v[70:73], v[176:179], v[22:25]
	v_mfma_f32_16x16x32_bf16 v[14:17], v[62:65], v[184:187], v[14:17]
	v_mfma_f32_16x16x32_bf16 v[6:9], v[70:73], v[184:187], v[6:9]
	v_mfma_f32_16x16x32_bf16 v[82:85], v[66:69], v[86:89], v[82:85]
	v_mfma_f32_16x16x32_bf16 v[54:57], v[74:77], v[86:89], v[54:57]
	v_mfma_f32_16x16x32_bf16 v[46:49], v[66:69], v[94:97], v[46:49]
	v_mfma_f32_16x16x32_bf16 v[38:41], v[74:77], v[94:97], v[38:41]
	v_mfma_f32_16x16x32_bf16 v[30:33], v[66:69], v[180:183], v[30:33]
	v_mfma_f32_16x16x32_bf16 v[22:25], v[74:77], v[180:183], v[22:25]
	v_mfma_f32_16x16x32_bf16 v[14:17], v[66:69], v[188:191], v[14:17]
	v_mfma_f32_16x16x32_bf16 v[6:9], v[74:77], v[188:191], v[6:9]
	s_setprio 0
	s_barrier
	s_add_u32 s36, s64, 0x40080
	s_addc_u32 s37, s65, 0
	s_add_i32 s64, s66, s68
	v_lshl_add_u64 v[62:63], s[36:37], 0, v[164:165]
	s_mov_b32 m0, s64
	s_nop 0
	global_load_lds_dwordx4 v[62:63], off
	v_lshl_add_u64 v[62:63], s[36:37], 0, v[162:163]
	s_add_i32 m0, s64, 0x2000
	s_nop 0
	global_load_lds_dwordx4 v[62:63], off
	s_waitcnt vmcnt(6)
	s_barrier
	s_setprio 1
	v_mfma_f32_16x16x32_bf16 v[58:61], v[208:211], v[78:81], v[58:61]
	v_mfma_f32_16x16x32_bf16 v[50:53], v[226:229], v[78:81], v[50:53]
	v_mfma_f32_16x16x32_bf16 v[42:45], v[208:211], v[90:93], v[42:45]
	v_mfma_f32_16x16x32_bf16 v[34:37], v[226:229], v[90:93], v[34:37]
	v_mfma_f32_16x16x32_bf16 v[26:29], v[208:211], v[176:179], v[26:29]
	v_mfma_f32_16x16x32_bf16 v[18:21], v[226:229], v[176:179], v[18:21]
	v_mfma_f32_16x16x32_bf16 v[10:13], v[208:211], v[184:187], v[10:13]
	v_mfma_f32_16x16x32_bf16 v[2:5], v[226:229], v[184:187], v[2:5]
	v_mfma_f32_16x16x32_bf16 v[74:77], v[222:225], v[86:89], v[58:61]
	v_mfma_f32_16x16x32_bf16 v[50:53], v[230:233], v[86:89], v[50:53]
	v_mfma_f32_16x16x32_bf16 v[42:45], v[222:225], v[94:97], v[42:45]
	v_mfma_f32_16x16x32_bf16 v[34:37], v[230:233], v[94:97], v[34:37]
	v_mfma_f32_16x16x32_bf16 v[26:29], v[222:225], v[180:183], v[26:29]
	v_mfma_f32_16x16x32_bf16 v[18:21], v[230:233], v[180:183], v[18:21]
	v_mfma_f32_16x16x32_bf16 v[10:13], v[222:225], v[188:191], v[10:13]
	v_mfma_f32_16x16x32_bf16 v[2:5], v[230:233], v[188:191], v[2:5]
	s_setprio 0
	s_add_i32 s83, s83, 2
	s_add_u32 s81, s81, 0x100
	s_addc_u32 s82, s82, 0
	s_cmp_gt_u32 s83, 13
	s_mov_b64 s[36:37], s[62:63]
	s_barrier
	.p2alignl 6, 3212836864

.LBB0_1178:
	s_add_u32 s27, s36, 0x100
	s_addc_u32 s91, s37, 0
	s_add_u32 s36, s42, 0x80
	s_addc_u32 s37, s43, 0
	s_mov_b32 s42, 0
	s_waitcnt lgkmcnt(0)
	s_add_i32 s92, s42, 2
	s_add_u32 s72, s36, 0x80
	s_addc_u32 s43, s37, 0
	s_add_i32 s93, 0, 0x10000
	v_add_u32_e32 v1, s93, v223
	ds_read_b128 v[50:53], v1
	ds_read_b128 v[54:57], v1 offset:1024
	ds_read_b128 v[58:61], v1 offset:2048
	ds_read_b128 v[62:65], v1 offset:3072
	s_cmp_eq_u32 s88, s42
	s_cselect_b32 s42, s66, s72
	s_cselect_b32 s43, s67, s43
	s_cselect_b32 s73, s71, s91
	s_cselect_b32 s72, s70, s27
	v_lshl_add_u64 v[178:179], s[36:37], 0, v[206:207]
	s_add_i32 m0, s79, 0xc000
	ds_read_b128 v[66:69], v230
	ds_read_b128 v[70:73], v230 offset:1024
	ds_read_b128 v[74:77], v230 offset:2048
	ds_read_b128 v[78:81], v230 offset:3072
	ds_read_b128 v[146:149], v230 offset:4096
	ds_read_b128 v[154:157], v230 offset:5120
	ds_read_b128 v[170:173], v230 offset:6144
	ds_read_b128 v[174:177], v230 offset:7168
	global_load_lds_dwordx4 v[178:179], off
	v_lshl_add_u64 v[178:179], s[36:37], 0, v[204:205]
	s_add_i32 m0, s79, 0xe000
	s_nop 0
	global_load_lds_dwordx4 v[178:179], off
	s_waitcnt lgkmcnt(8)
	s_barrier
	s_waitcnt lgkmcnt(0)
	s_setprio 1
	s_waitcnt lgkmcnt(0)
	v_mfma_f32_16x16x32_bf16 v[166:169], v[50:53], v[66:69], 0
	v_mfma_f32_16x16x32_bf16 v[162:165], v[58:61], v[66:69], 0
	v_mfma_f32_16x16x32_bf16 v[142:145], v[50:53], v[74:77], 0
	v_mfma_f32_16x16x32_bf16 v[138:141], v[58:61], v[74:77], 0
	v_mfma_f32_16x16x32_bf16 v[126:129], v[50:53], v[146:149], 0
	v_mfma_f32_16x16x32_bf16 v[122:125], v[58:61], v[146:149], 0
	v_mfma_f32_16x16x32_bf16 v[110:113], v[50:53], v[170:173], 0
	v_mfma_f32_16x16x32_bf16 v[106:109], v[58:61], v[170:173], 0
	v_mfma_f32_16x16x32_bf16 v[166:169], v[54:57], v[70:73], v[166:169]
	v_mfma_f32_16x16x32_bf16 v[162:165], v[62:65], v[70:73], v[162:165]
	v_mfma_f32_16x16x32_bf16 v[142:145], v[54:57], v[78:81], v[142:145]
	v_mfma_f32_16x16x32_bf16 v[138:141], v[62:65], v[78:81], v[138:141]
	v_mfma_f32_16x16x32_bf16 v[126:129], v[54:57], v[154:157], v[126:129]
	v_mfma_f32_16x16x32_bf16 v[122:125], v[62:65], v[154:157], v[122:125]
	v_mfma_f32_16x16x32_bf16 v[110:113], v[54:57], v[174:177], v[110:113]
	v_mfma_f32_16x16x32_bf16 v[106:109], v[62:65], v[174:177], v[106:109]
	s_setprio 0
	s_barrier
	s_add_i32 s94, 0, 0x14000
	s_add_i32 s93, s93, s78
	v_add_u32_e32 v1, s94, v223
	v_lshl_add_u64 v[214:215], s[72:73], 0, v[202:203]
	s_mov_b32 m0, s93
	ds_read_b128 v[178:181], v1
	ds_read_b128 v[182:185], v1 offset:1024
	ds_read_b128 v[186:189], v1 offset:2048
	ds_read_b128 v[190:193], v1 offset:3072
	global_load_lds_dwordx4 v[214:215], off
	v_lshl_add_u64 v[236:237], s[72:73], 0, v[200:201]
	s_add_i32 m0, s93, 0x2000
	s_nop 0
	global_load_lds_dwordx4 v[236:237], off
	s_barrier
	s_waitcnt lgkmcnt(0)
	s_setprio 1
	s_waitcnt lgkmcnt(0)
	v_mfma_f32_16x16x32_bf16 v[158:161], v[178:181], v[66:69], 0
	v_mfma_f32_16x16x32_bf16 v[66:69], v[186:189], v[66:69], 0
	v_mfma_f32_16x16x32_bf16 v[158:161], v[182:185], v[70:73], v[158:161]
	v_mfma_f32_16x16x32_bf16 v[66:69], v[190:193], v[70:73], v[66:69]
	v_mfma_f32_16x16x32_bf16 v[70:73], v[178:181], v[74:77], 0
	v_mfma_f32_16x16x32_bf16 v[74:77], v[186:189], v[74:77], 0
	v_mfma_f32_16x16x32_bf16 v[114:117], v[186:189], v[146:149], 0
	v_mfma_f32_16x16x32_bf16 v[102:105], v[178:181], v[170:173], 0
	v_mfma_f32_16x16x32_bf16 v[98:101], v[186:189], v[170:173], 0
	v_mfma_f32_16x16x32_bf16 v[70:73], v[182:185], v[78:81], v[70:73]
	v_mfma_f32_16x16x32_bf16 v[74:77], v[190:193], v[78:81], v[74:77]
	v_mfma_f32_16x16x32_bf16 v[78:81], v[178:181], v[146:149], 0
	v_mfma_f32_16x16x32_bf16 v[114:117], v[190:193], v[154:157], v[114:117]
	v_mfma_f32_16x16x32_bf16 v[102:105], v[182:185], v[174:177], v[102:105]
	v_mfma_f32_16x16x32_bf16 v[98:101], v[190:193], v[174:177], v[98:101]
	v_mfma_f32_16x16x32_bf16 v[78:81], v[182:185], v[154:157], v[78:81]
	s_setprio 0
	s_mov_b32 m0, s79
	v_lshl_add_u64 v[238:239], s[42:43], 0, v[202:203]
	s_barrier
	ds_read_b128 v[118:121], v230 offset:16384
	ds_read_b128 v[130:133], v230 offset:17408
	ds_read_b128 v[134:137], v230 offset:18432
	ds_read_b128 v[146:149], v230 offset:19456
	ds_read_b128 v[150:153], v230 offset:20480
	ds_read_b128 v[154:157], v230 offset:21504
	ds_read_b128 v[170:173], v230 offset:22528
	ds_read_b128 v[174:177], v230 offset:23552
	global_load_lds_dwordx4 v[238:239], off
	v_lshl_add_u64 v[240:241], s[42:43], 0, v[200:201]
	s_mov_b32 m0, s80
	s_nop 0
	global_load_lds_dwordx4 v[240:241], off
	s_barrier
	s_waitcnt lgkmcnt(0)
	s_setprio 1
	s_waitcnt lgkmcnt(0)
	v_mfma_f32_16x16x32_bf16 v[94:97], v[50:53], v[118:121], 0
	v_mfma_f32_16x16x32_bf16 v[90:93], v[58:61], v[118:121], 0
	v_mfma_f32_16x16x32_bf16 v[46:49], v[50:53], v[134:137], 0
	v_mfma_f32_16x16x32_bf16 v[42:45], v[58:61], v[134:137], 0
	v_mfma_f32_16x16x32_bf16 v[30:33], v[50:53], v[150:153], 0
	v_mfma_f32_16x16x32_bf16 v[26:29], v[58:61], v[150:153], 0
	v_mfma_f32_16x16x32_bf16 v[14:17], v[50:53], v[170:173], 0
	v_mfma_f32_16x16x32_bf16 v[10:13], v[58:61], v[170:173], 0
	v_mfma_f32_16x16x32_bf16 v[94:97], v[54:57], v[130:133], v[94:97]
	v_mfma_f32_16x16x32_bf16 v[90:93], v[62:65], v[130:133], v[90:93]
	v_mfma_f32_16x16x32_bf16 v[46:49], v[54:57], v[146:149], v[46:49]
	v_mfma_f32_16x16x32_bf16 v[42:45], v[62:65], v[146:149], v[42:45]
	v_mfma_f32_16x16x32_bf16 v[30:33], v[54:57], v[154:157], v[30:33]
	v_mfma_f32_16x16x32_bf16 v[26:29], v[62:65], v[154:157], v[26:29]
	v_mfma_f32_16x16x32_bf16 v[14:17], v[54:57], v[174:177], v[14:17]
	v_mfma_f32_16x16x32_bf16 v[10:13], v[62:65], v[174:177], v[10:13]
	s_setprio 0
	s_barrier
	s_add_u32 s72, s72, s4
	s_addc_u32 s73, s73, 0
	s_add_i32 s93, s94, s78
	v_lshl_add_u64 v[242:243], s[72:73], 0, v[202:203]
	s_mov_b32 m0, s93
	v_lshl_add_u64 v[244:245], s[72:73], 0, v[200:201]
	global_load_lds_dwordx4 v[242:243], off
	s_add_i32 m0, s93, 0x2000
	s_nop 0
	global_load_lds_dwordx4 v[244:245], off
	s_waitcnt vmcnt(6)
	s_barrier
	s_setprio 1
	v_mfma_f32_16x16x32_bf16 v[38:41], v[178:181], v[134:137], 0
	v_mfma_f32_16x16x32_bf16 v[34:37], v[186:189], v[134:137], 0
	v_mfma_f32_16x16x32_bf16 v[22:25], v[178:181], v[150:153], 0
	v_mfma_f32_16x16x32_bf16 v[18:21], v[186:189], v[150:153], 0
	v_mfma_f32_16x16x32_bf16 v[6:9], v[178:181], v[170:173], 0
	v_mfma_f32_16x16x32_bf16 v[2:5], v[186:189], v[170:173], 0
	v_mfma_f32_16x16x32_bf16 v[50:53], v[178:181], v[118:121], 0
	v_mfma_f32_16x16x32_bf16 v[54:57], v[186:189], v[118:121], 0
	v_mfma_f32_16x16x32_bf16 v[38:41], v[182:185], v[146:149], v[38:41]
	v_mfma_f32_16x16x32_bf16 v[34:37], v[190:193], v[146:149], v[34:37]
	v_mfma_f32_16x16x32_bf16 v[22:25], v[182:185], v[154:157], v[22:25]
	v_mfma_f32_16x16x32_bf16 v[18:21], v[190:193], v[154:157], v[18:21]
	v_mfma_f32_16x16x32_bf16 v[6:9], v[182:185], v[174:177], v[6:9]
	v_mfma_f32_16x16x32_bf16 v[2:5], v[190:193], v[174:177], v[2:5]
	v_mfma_f32_16x16x32_bf16 v[50:53], v[182:185], v[130:133], v[50:53]
	v_mfma_f32_16x16x32_bf16 v[54:57], v[190:193], v[130:133], v[54:57]
	s_setprio 0
	s_add_i32 s72, 0, 0x18000
	v_add_u32_e32 v1, s72, v223
	s_barrier
	ds_read_b128 v[58:61], v1
	ds_read_b128 v[62:65], v1 offset:1024
	ds_read_b128 v[82:85], v1 offset:2048
	ds_read_b128 v[86:89], v1 offset:3072
	s_add_u32 s42, s42, s4
	s_addc_u32 s43, s43, 0
	s_mov_b32 m0, s81
	v_lshl_add_u64 v[134:135], s[42:43], 0, v[202:203]
	ds_read_b128 v[118:121], v230 offset:32768
	ds_read_b128 v[130:133], v230 offset:33792
	ds_read_b128 v[146:149], v230 offset:34816
	ds_read_b128 v[154:157], v230 offset:35840
	ds_read_b128 v[170:173], v230 offset:36864
	ds_read_b128 v[174:177], v230 offset:37888
	ds_read_b128 v[178:181], v230 offset:38912
	ds_read_b128 v[182:185], v230 offset:39936
	global_load_lds_dwordx4 v[134:135], off
	v_lshl_add_u64 v[134:135], s[42:43], 0, v[200:201]
	s_mov_b32 m0, s82
	s_nop 0
	global_load_lds_dwordx4 v[134:135], off
	s_waitcnt lgkmcnt(8)
	s_barrier
	s_waitcnt lgkmcnt(0)
	s_setprio 1
	s_waitcnt lgkmcnt(0)
	v_mfma_f32_16x16x32_bf16 v[134:137], v[58:61], v[118:121], v[166:169]
	v_mfma_f32_16x16x32_bf16 v[166:169], v[62:65], v[130:133], v[134:137]
	v_mfma_f32_16x16x32_bf16 v[134:137], v[82:85], v[118:121], v[162:165]
	v_mfma_f32_16x16x32_bf16 v[162:165], v[86:89], v[130:133], v[134:137]
	v_mfma_f32_16x16x32_bf16 v[134:137], v[58:61], v[146:149], v[142:145]
	v_mfma_f32_16x16x32_bf16 v[142:145], v[62:65], v[154:157], v[134:137]
	v_mfma_f32_16x16x32_bf16 v[134:137], v[82:85], v[146:149], v[138:141]
	v_mfma_f32_16x16x32_bf16 v[126:129], v[58:61], v[170:173], v[126:129]
	v_mfma_f32_16x16x32_bf16 v[122:125], v[82:85], v[170:173], v[122:125]
	v_mfma_f32_16x16x32_bf16 v[110:113], v[58:61], v[178:181], v[110:113]
	v_mfma_f32_16x16x32_bf16 v[106:109], v[82:85], v[178:181], v[106:109]
	v_mfma_f32_16x16x32_bf16 v[138:141], v[86:89], v[154:157], v[134:137]
	v_mfma_f32_16x16x32_bf16 v[126:129], v[62:65], v[174:177], v[126:129]
	v_mfma_f32_16x16x32_bf16 v[122:125], v[86:89], v[174:177], v[122:125]
	v_mfma_f32_16x16x32_bf16 v[110:113], v[62:65], v[182:185], v[110:113]
	v_mfma_f32_16x16x32_bf16 v[106:109], v[86:89], v[182:185], v[106:109]
	s_setprio 0
	s_barrier
	s_add_i32 s42, 0, 0x1c000
	s_add_i32 s43, s72, s78
	v_add_u32_e32 v1, s42, v223
	v_lshl_add_u64 v[134:135], v[214:215], 0, s[22:23]
	s_mov_b32 m0, s43
	ds_read_b128 v[186:189], v1
	ds_read_b128 v[190:193], v1 offset:1024
	ds_read_b128 v[208:211], v1 offset:2048
	ds_read_b128 v[232:235], v1 offset:3072
	global_load_lds_dwordx4 v[134:135], off
	v_lshl_add_u64 v[134:135], v[236:237], 0, s[22:23]
	s_add_i32 m0, s43, 0x2000
	s_nop 0
	global_load_lds_dwordx4 v[134:135], off
	s_barrier
	s_waitcnt lgkmcnt(0)
	s_setprio 1
	s_waitcnt lgkmcnt(0)
	v_mfma_f32_16x16x32_bf16 v[66:69], v[208:211], v[118:121], v[66:69]
	v_mfma_f32_16x16x32_bf16 v[134:137], v[186:189], v[118:121], v[158:161]
	v_mfma_f32_16x16x32_bf16 v[150:153], v[232:235], v[130:133], v[66:69]
	v_mfma_f32_16x16x32_bf16 v[66:69], v[186:189], v[146:149], v[70:73]
	v_mfma_f32_16x16x32_bf16 v[158:161], v[190:193], v[130:133], v[134:137]
	v_mfma_f32_16x16x32_bf16 v[134:137], v[190:193], v[154:157], v[66:69]
	v_mfma_f32_16x16x32_bf16 v[66:69], v[208:211], v[146:149], v[74:77]
	v_mfma_f32_16x16x32_bf16 v[130:133], v[232:235], v[154:157], v[66:69]
	v_mfma_f32_16x16x32_bf16 v[66:69], v[186:189], v[170:173], v[78:81]
	v_mfma_f32_16x16x32_bf16 v[118:121], v[190:193], v[174:177], v[66:69]
	v_mfma_f32_16x16x32_bf16 v[66:69], v[208:211], v[170:173], v[114:117]
	v_mfma_f32_16x16x32_bf16 v[114:117], v[232:235], v[174:177], v[66:69]
	v_mfma_f32_16x16x32_bf16 v[66:69], v[186:189], v[178:181], v[102:105]
	v_mfma_f32_16x16x32_bf16 v[102:105], v[190:193], v[182:185], v[66:69]
	v_mfma_f32_16x16x32_bf16 v[66:69], v[208:211], v[178:181], v[98:101]
	v_mfma_f32_16x16x32_bf16 v[98:101], v[232:235], v[182:185], v[66:69]
	s_setprio 0
	s_mov_b32 m0, s86
	v_lshl_add_u64 v[178:179], v[238:239], 0, s[22:23]
	s_barrier
	s_nop 2
	ds_read_b128 v[66:69], v230 offset:49152
	ds_read_b128 v[70:73], v230 offset:50176
	ds_read_b128 v[74:77], v230 offset:51200
	ds_read_b128 v[78:81], v230 offset:52224
	ds_read_b128 v[146:149], v230 offset:53248
	ds_read_b128 v[154:157], v230 offset:54272
	ds_read_b128 v[170:173], v230 offset:55296
	ds_read_b128 v[174:177], v230 offset:56320
	global_load_lds_dwordx4 v[178:179], off
	v_lshl_add_u64 v[178:179], v[240:241], 0, s[22:23]
	s_mov_b32 m0, s87
	s_nop 0
	global_load_lds_dwordx4 v[178:179], off
	s_barrier
	s_waitcnt lgkmcnt(0)
	s_setprio 1
	s_waitcnt lgkmcnt(0)
	v_mfma_f32_16x16x32_bf16 v[94:97], v[58:61], v[66:69], v[94:97]
	v_mfma_f32_16x16x32_bf16 v[90:93], v[82:85], v[66:69], v[90:93]
	v_mfma_f32_16x16x32_bf16 v[46:49], v[58:61], v[74:77], v[46:49]
	v_mfma_f32_16x16x32_bf16 v[42:45], v[82:85], v[74:77], v[42:45]
	v_mfma_f32_16x16x32_bf16 v[30:33], v[58:61], v[146:149], v[30:33]
	v_mfma_f32_16x16x32_bf16 v[26:29], v[82:85], v[146:149], v[26:29]
	v_mfma_f32_16x16x32_bf16 v[14:17], v[58:61], v[170:173], v[14:17]
	v_mfma_f32_16x16x32_bf16 v[10:13], v[82:85], v[170:173], v[10:13]
	v_mfma_f32_16x16x32_bf16 v[94:97], v[62:65], v[70:73], v[94:97]
	v_mfma_f32_16x16x32_bf16 v[90:93], v[86:89], v[70:73], v[90:93]
	v_mfma_f32_16x16x32_bf16 v[46:49], v[62:65], v[78:81], v[46:49]
	v_mfma_f32_16x16x32_bf16 v[42:45], v[86:89], v[78:81], v[42:45]
	v_mfma_f32_16x16x32_bf16 v[30:33], v[62:65], v[154:157], v[30:33]
	v_mfma_f32_16x16x32_bf16 v[26:29], v[86:89], v[154:157], v[26:29]
	v_mfma_f32_16x16x32_bf16 v[14:17], v[62:65], v[174:177], v[14:17]
	v_mfma_f32_16x16x32_bf16 v[10:13], v[86:89], v[174:177], v[10:13]
	s_setprio 0
	s_barrier
	s_add_i32 s42, s42, s78
	v_lshl_add_u64 v[58:59], v[242:243], 0, s[22:23]
	s_mov_b32 m0, s42
	s_nop 0
	global_load_lds_dwordx4 v[58:59], off
	v_lshl_add_u64 v[58:59], v[244:245], 0, s[22:23]
	s_add_i32 m0, s42, 0x2000
	s_nop 0
	global_load_lds_dwordx4 v[58:59], off
	s_waitcnt vmcnt(6)
	s_barrier
	s_setprio 1
	v_mfma_f32_16x16x32_bf16 v[50:53], v[186:189], v[66:69], v[50:53]
	v_mfma_f32_16x16x32_bf16 v[86:89], v[190:193], v[70:73], v[50:53]
	v_mfma_f32_16x16x32_bf16 v[50:53], v[208:211], v[66:69], v[54:57]
	v_mfma_f32_16x16x32_bf16 v[38:41], v[186:189], v[74:77], v[38:41]
	v_mfma_f32_16x16x32_bf16 v[34:37], v[208:211], v[74:77], v[34:37]
	v_mfma_f32_16x16x32_bf16 v[22:25], v[186:189], v[146:149], v[22:25]
	v_mfma_f32_16x16x32_bf16 v[18:21], v[208:211], v[146:149], v[18:21]
	v_mfma_f32_16x16x32_bf16 v[6:9], v[186:189], v[170:173], v[6:9]
	v_mfma_f32_16x16x32_bf16 v[2:5], v[208:211], v[170:173], v[2:5]
	v_mfma_f32_16x16x32_bf16 v[82:85], v[232:235], v[70:73], v[50:53]
	v_mfma_f32_16x16x32_bf16 v[38:41], v[190:193], v[78:81], v[38:41]
	v_mfma_f32_16x16x32_bf16 v[34:37], v[232:235], v[78:81], v[34:37]
	v_mfma_f32_16x16x32_bf16 v[22:25], v[190:193], v[154:157], v[22:25]
	v_mfma_f32_16x16x32_bf16 v[18:21], v[232:235], v[154:157], v[18:21]
	v_mfma_f32_16x16x32_bf16 v[6:9], v[190:193], v[174:177], v[6:9]
	v_mfma_f32_16x16x32_bf16 v[2:5], v[232:235], v[174:177], v[2:5]
	s_setprio 0
	s_add_u32 s27, s27, 0x100
	s_addc_u32 s91, s91, 0
	s_add_u32 s36, s36, 0x100
	s_addc_u32 s37, s37, 0
	s_cmp_ge_u32 s92, s84
	s_mov_b32 s42, s92
	s_barrier
	.p2alignl 6, 3212836864
